# hand-written packed-f32 gate-up epilogue (same op order, 4 outputs per dependency group, stepped 64-bit pointer) on top of k33
# speedup vs baseline: 1.0068x; 1.0068x over previous
; __device__ __forceinline__ unsigned cvt_pk_bf16(float lo, float hi) { const f32x2_t v = {lo, hi}; const bf16x2_t b = __builtin_convertvector(v, bf16x2_t); return __builtin_bit_cast(unsigned, b); }
; __device__ __forceinline__ float sigmoidf_(float x) { return __builtin_amdgcn_rcpf(1.0f + __expf(-x)); }
;     __device__ __forceinline__ void operator()(const Acc& acc, const Unit& u, int wr, int wc, int fr, int fq) const {
;     ...
;             for (int m = 0; m < 4; ++m) { const int row = u.pm * 256 + ai * 128 + wr * 64 + m * 16 + fr;
;                 const int col = u.pn * 128 + wc * 32 + fq * 8; u32x4 w;
; #pragma unroll
;                 for (int n = 0; n < 2; ++n) { const f32x4 g = acc[ai][0][m][n], up = acc[ai][1][m][n]; f32x4 h;
; #pragma unroll
;                     for (int i = 0; i < 4; ++i) h[i] = g[i] * sigmoidf_(g[i]) * up[i];
;                     w[2 * n] = cvt_pk_bf16(h[0], h[1]); w[2 * n + 1] = cvt_pk_bf16(h[2], h[3]); }
;                 *(u32x4*)(H + (size_t)row * DFF + col) = w; }
.LBB0_1792:
	s_lshl_b32 s11, s44, 8
	s_add_i32 s11, s11, s38
	v_add_u32_e32 v143, s11, v139
	s_lshl_b32 s11, s45, 7
	s_or_b32 s11, s11, s39
	v_lshl_add_u32 v144, v140, 3, s11
	v_ashrrev_i32_e32 v145, 31, v144
	v_mov_b64_e32 v[146:147], s[6:7]
	s_movk_i32 s11, 0x1600
	s_nop 0
	v_mad_i64_i32 v[146:147], s[18:19], v143, s11, v[146:147]
	v_lshlrev_b64 v[148:149], 1, v[144:145]
	v_lshl_add_u64 v[146:147], v[146:147], 0, v[148:149]
	s_mov_b32 s20, 0x16000
	s_mov_b32 s21, 0x0
	s_mov_b32 s22, 0x6e000
	s_mov_b32 s23, 0x0
	s_mov_b32 s46, 0xbfb8aa3b
	s_mov_b32 s47, 0xbfb8aa3b
	v_pk_mul_f32 v[150:151], v[124:125], s[46:47]
	v_pk_mul_f32 v[152:153], v[126:127], s[46:47]
	v_pk_mul_f32 v[154:155], v[116:117], s[46:47]
	v_pk_mul_f32 v[156:157], v[118:119], s[46:47]
	v_exp_f32_e32 v150, v150
	v_exp_f32_e32 v151, v151
	v_exp_f32_e32 v152, v152
	v_exp_f32_e32 v153, v153
	v_exp_f32_e32 v154, v154
	v_exp_f32_e32 v155, v155
	v_exp_f32_e32 v156, v156
	v_exp_f32_e32 v157, v157
	v_pk_add_f32 v[150:151], v[150:151], 1.0 op_sel_hi:[1,0]
	v_pk_add_f32 v[152:153], v[152:153], 1.0 op_sel_hi:[1,0]
	v_pk_add_f32 v[154:155], v[154:155], 1.0 op_sel_hi:[1,0]
	v_pk_add_f32 v[156:157], v[156:157], 1.0 op_sel_hi:[1,0]
	v_rcp_f32_e32 v150, v150
	v_rcp_f32_e32 v151, v151
	v_rcp_f32_e32 v152, v152
	v_rcp_f32_e32 v153, v153
	v_rcp_f32_e32 v154, v154
	v_rcp_f32_e32 v155, v155
	v_rcp_f32_e32 v156, v156
	v_rcp_f32_e32 v157, v157
	v_pk_mul_f32 v[124:125], v[124:125], v[150:151]
	v_pk_mul_f32 v[126:127], v[126:127], v[152:153]
	v_pk_mul_f32 v[116:117], v[116:117], v[154:155]
	v_pk_mul_f32 v[118:119], v[118:119], v[156:157]
	v_pk_mul_f32 v[120:121], v[120:121], v[124:125]
	v_pk_mul_f32 v[122:123], v[122:123], v[126:127]
	v_pk_mul_f32 v[112:113], v[112:113], v[116:117]
	v_pk_mul_f32 v[114:115], v[114:115], v[118:119]
	v_cvt_pk_bf16_f32 v120, v120, v121
	v_cvt_pk_bf16_f32 v121, v122, v123
	v_cvt_pk_bf16_f32 v122, v112, v113
	v_cvt_pk_bf16_f32 v123, v114, v115
	global_store_dwordx4 v[146:147], v[120:123], off
	v_lshl_add_u64 v[146:147], v[146:147], 0, s[20:21]
	v_pk_mul_f32 v[150:151], v[108:109], s[46:47]
	v_pk_mul_f32 v[152:153], v[110:111], s[46:47]
	v_pk_mul_f32 v[154:155], v[100:101], s[46:47]
	v_pk_mul_f32 v[156:157], v[102:103], s[46:47]
	v_exp_f32_e32 v150, v150
	v_exp_f32_e32 v151, v151
	v_exp_f32_e32 v152, v152
	v_exp_f32_e32 v153, v153
	v_exp_f32_e32 v154, v154
	v_exp_f32_e32 v155, v155
	v_exp_f32_e32 v156, v156
	v_exp_f32_e32 v157, v157
	v_pk_add_f32 v[150:151], v[150:151], 1.0 op_sel_hi:[1,0]
	v_pk_add_f32 v[152:153], v[152:153], 1.0 op_sel_hi:[1,0]
	v_pk_add_f32 v[154:155], v[154:155], 1.0 op_sel_hi:[1,0]
	v_pk_add_f32 v[156:157], v[156:157], 1.0 op_sel_hi:[1,0]
	v_rcp_f32_e32 v150, v150
	v_rcp_f32_e32 v151, v151
	v_rcp_f32_e32 v152, v152
	v_rcp_f32_e32 v153, v153
	v_rcp_f32_e32 v154, v154
	v_rcp_f32_e32 v155, v155
	v_rcp_f32_e32 v156, v156
	v_rcp_f32_e32 v157, v157
	v_pk_mul_f32 v[108:109], v[108:109], v[150:151]
	v_pk_mul_f32 v[110:111], v[110:111], v[152:153]
	v_pk_mul_f32 v[100:101], v[100:101], v[154:155]
	v_pk_mul_f32 v[102:103], v[102:103], v[156:157]
	v_pk_mul_f32 v[104:105], v[104:105], v[108:109]
	v_pk_mul_f32 v[106:107], v[106:107], v[110:111]
	v_pk_mul_f32 v[96:97], v[96:97], v[100:101]
	v_pk_mul_f32 v[98:99], v[98:99], v[102:103]
	v_cvt_pk_bf16_f32 v104, v104, v105
	v_cvt_pk_bf16_f32 v105, v106, v107
	v_cvt_pk_bf16_f32 v106, v96, v97
	v_cvt_pk_bf16_f32 v107, v98, v99
	global_store_dwordx4 v[146:147], v[104:107], off
	v_lshl_add_u64 v[146:147], v[146:147], 0, s[20:21]
	v_pk_mul_f32 v[150:151], v[92:93], s[46:47]
	v_pk_mul_f32 v[152:153], v[94:95], s[46:47]
	v_pk_mul_f32 v[154:155], v[84:85], s[46:47]
	v_pk_mul_f32 v[156:157], v[86:87], s[46:47]
	v_exp_f32_e32 v150, v150
	v_exp_f32_e32 v151, v151
	v_exp_f32_e32 v152, v152
	v_exp_f32_e32 v153, v153
	v_exp_f32_e32 v154, v154
	v_exp_f32_e32 v155, v155
	v_exp_f32_e32 v156, v156
	v_exp_f32_e32 v157, v157
	v_pk_add_f32 v[150:151], v[150:151], 1.0 op_sel_hi:[1,0]
	v_pk_add_f32 v[152:153], v[152:153], 1.0 op_sel_hi:[1,0]
	v_pk_add_f32 v[154:155], v[154:155], 1.0 op_sel_hi:[1,0]
	v_pk_add_f32 v[156:157], v[156:157], 1.0 op_sel_hi:[1,0]
	v_rcp_f32_e32 v150, v150
	v_rcp_f32_e32 v151, v151
	v_rcp_f32_e32 v152, v152
	v_rcp_f32_e32 v153, v153
	v_rcp_f32_e32 v154, v154
	v_rcp_f32_e32 v155, v155
	v_rcp_f32_e32 v156, v156
	v_rcp_f32_e32 v157, v157
	v_pk_mul_f32 v[92:93], v[92:93], v[150:151]
	v_pk_mul_f32 v[94:95], v[94:95], v[152:153]
	v_pk_mul_f32 v[84:85], v[84:85], v[154:155]
	v_pk_mul_f32 v[86:87], v[86:87], v[156:157]
	v_pk_mul_f32 v[88:89], v[88:89], v[92:93]
	v_pk_mul_f32 v[90:91], v[90:91], v[94:95]
	v_pk_mul_f32 v[80:81], v[80:81], v[84:85]
	v_pk_mul_f32 v[82:83], v[82:83], v[86:87]
	v_cvt_pk_bf16_f32 v88, v88, v89
	v_cvt_pk_bf16_f32 v89, v90, v91
	v_cvt_pk_bf16_f32 v90, v80, v81
	v_cvt_pk_bf16_f32 v91, v82, v83
	global_store_dwordx4 v[146:147], v[88:91], off
	v_lshl_add_u64 v[146:147], v[146:147], 0, s[20:21]
	v_pk_mul_f32 v[150:151], v[76:77], s[46:47]
	v_pk_mul_f32 v[152:153], v[78:79], s[46:47]
	v_pk_mul_f32 v[154:155], v[68:69], s[46:47]
	v_pk_mul_f32 v[156:157], v[70:71], s[46:47]
	v_exp_f32_e32 v150, v150
	v_exp_f32_e32 v151, v151
	v_exp_f32_e32 v152, v152
	v_exp_f32_e32 v153, v153
	v_exp_f32_e32 v154, v154
	v_exp_f32_e32 v155, v155
	v_exp_f32_e32 v156, v156
	v_exp_f32_e32 v157, v157
	v_pk_add_f32 v[150:151], v[150:151], 1.0 op_sel_hi:[1,0]
	v_pk_add_f32 v[152:153], v[152:153], 1.0 op_sel_hi:[1,0]
	v_pk_add_f32 v[154:155], v[154:155], 1.0 op_sel_hi:[1,0]
	v_pk_add_f32 v[156:157], v[156:157], 1.0 op_sel_hi:[1,0]
	v_rcp_f32_e32 v150, v150
	v_rcp_f32_e32 v151, v151
	v_rcp_f32_e32 v152, v152
	v_rcp_f32_e32 v153, v153
; __device__ __forceinline__ unsigned cvt_pk_bf16(float lo, float hi) { const f32x2_t v = {lo, hi}; const bf16x2_t b = __builtin_convertvector(v, bf16x2_t); return __builtin_bit_cast(unsigned, b); }
; __device__ __forceinline__ float sigmoidf_(float x) { return __builtin_amdgcn_rcpf(1.0f + __expf(-x)); }
;     __device__ __forceinline__ void operator()(const Acc& acc, const Unit& u, int wr, int wc, int fr, int fq) const {
;     ...
;             for (int m = 0; m < 4; ++m) { const int row = u.pm * 256 + ai * 128 + wr * 64 + m * 16 + fr;
;                 const int col = u.pn * 128 + wc * 32 + fq * 8; u32x4 w;
; #pragma unroll
;                 for (int n = 0; n < 2; ++n) { const f32x4 g = acc[ai][0][m][n], up = acc[ai][1][m][n]; f32x4 h;
; #pragma unroll
;                     for (int i = 0; i < 4; ++i) h[i] = g[i] * sigmoidf_(g[i]) * up[i];
;                     w[2 * n] = cvt_pk_bf16(h[0], h[1]); w[2 * n + 1] = cvt_pk_bf16(h[2], h[3]); }
;                 *(u32x4*)(H + (size_t)row * DFF + col) = w; }
	v_rcp_f32_e32 v154, v154
	v_rcp_f32_e32 v155, v155
	v_rcp_f32_e32 v156, v156
	v_rcp_f32_e32 v157, v157
	v_pk_mul_f32 v[76:77], v[76:77], v[150:151]
	v_pk_mul_f32 v[78:79], v[78:79], v[152:153]
	v_pk_mul_f32 v[68:69], v[68:69], v[154:155]
	v_pk_mul_f32 v[70:71], v[70:71], v[156:157]
	v_pk_mul_f32 v[72:73], v[72:73], v[76:77]
	v_pk_mul_f32 v[74:75], v[74:75], v[78:79]
	v_pk_mul_f32 v[64:65], v[64:65], v[68:69]
	v_pk_mul_f32 v[66:67], v[66:67], v[70:71]
	v_cvt_pk_bf16_f32 v72, v72, v73
	v_cvt_pk_bf16_f32 v73, v74, v75
	v_cvt_pk_bf16_f32 v74, v64, v65
	v_cvt_pk_bf16_f32 v75, v66, v67
	global_store_dwordx4 v[146:147], v[72:75], off
	v_lshl_add_u64 v[146:147], v[146:147], 0, s[22:23]
	v_pk_mul_f32 v[150:151], v[60:61], s[46:47]
	v_pk_mul_f32 v[152:153], v[62:63], s[46:47]
	v_pk_mul_f32 v[154:155], v[52:53], s[46:47]
	v_pk_mul_f32 v[156:157], v[54:55], s[46:47]
	v_exp_f32_e32 v150, v150
	v_exp_f32_e32 v151, v151
	v_exp_f32_e32 v152, v152
	v_exp_f32_e32 v153, v153
	v_exp_f32_e32 v154, v154
	v_exp_f32_e32 v155, v155
	v_exp_f32_e32 v156, v156
	v_exp_f32_e32 v157, v157
	v_pk_add_f32 v[150:151], v[150:151], 1.0 op_sel_hi:[1,0]
	v_pk_add_f32 v[152:153], v[152:153], 1.0 op_sel_hi:[1,0]
	v_pk_add_f32 v[154:155], v[154:155], 1.0 op_sel_hi:[1,0]
	v_pk_add_f32 v[156:157], v[156:157], 1.0 op_sel_hi:[1,0]
	v_rcp_f32_e32 v150, v150
	v_rcp_f32_e32 v151, v151
	v_rcp_f32_e32 v152, v152
	v_rcp_f32_e32 v153, v153
	v_rcp_f32_e32 v154, v154
	v_rcp_f32_e32 v155, v155
	v_rcp_f32_e32 v156, v156
	v_rcp_f32_e32 v157, v157
	v_pk_mul_f32 v[60:61], v[60:61], v[150:151]
	v_pk_mul_f32 v[62:63], v[62:63], v[152:153]
	v_pk_mul_f32 v[52:53], v[52:53], v[154:155]
	v_pk_mul_f32 v[54:55], v[54:55], v[156:157]
	v_pk_mul_f32 v[56:57], v[56:57], v[60:61]
	v_pk_mul_f32 v[58:59], v[58:59], v[62:63]
	v_pk_mul_f32 v[48:49], v[48:49], v[52:53]
	v_pk_mul_f32 v[50:51], v[50:51], v[54:55]
	v_cvt_pk_bf16_f32 v56, v56, v57
	v_cvt_pk_bf16_f32 v57, v58, v59
	v_cvt_pk_bf16_f32 v58, v48, v49
	v_cvt_pk_bf16_f32 v59, v50, v51
	global_store_dwordx4 v[146:147], v[56:59], off
	v_lshl_add_u64 v[146:147], v[146:147], 0, s[20:21]
	v_pk_mul_f32 v[150:151], v[44:45], s[46:47]
	v_pk_mul_f32 v[152:153], v[46:47], s[46:47]
	v_pk_mul_f32 v[154:155], v[36:37], s[46:47]
	v_pk_mul_f32 v[156:157], v[38:39], s[46:47]
	v_exp_f32_e32 v150, v150
	v_exp_f32_e32 v151, v151
	v_exp_f32_e32 v152, v152
	v_exp_f32_e32 v153, v153
	v_exp_f32_e32 v154, v154
	v_exp_f32_e32 v155, v155
	v_exp_f32_e32 v156, v156
	v_exp_f32_e32 v157, v157
	v_pk_add_f32 v[150:151], v[150:151], 1.0 op_sel_hi:[1,0]
	v_pk_add_f32 v[152:153], v[152:153], 1.0 op_sel_hi:[1,0]
	v_pk_add_f32 v[154:155], v[154:155], 1.0 op_sel_hi:[1,0]
	v_pk_add_f32 v[156:157], v[156:157], 1.0 op_sel_hi:[1,0]
	v_rcp_f32_e32 v150, v150
	v_rcp_f32_e32 v151, v151
	v_rcp_f32_e32 v152, v152
	v_rcp_f32_e32 v153, v153
	v_rcp_f32_e32 v154, v154
	v_rcp_f32_e32 v155, v155
	v_rcp_f32_e32 v156, v156
	v_rcp_f32_e32 v157, v157
	v_pk_mul_f32 v[44:45], v[44:45], v[150:151]
	v_pk_mul_f32 v[46:47], v[46:47], v[152:153]
	v_pk_mul_f32 v[36:37], v[36:37], v[154:155]
	v_pk_mul_f32 v[38:39], v[38:39], v[156:157]
	v_pk_mul_f32 v[40:41], v[40:41], v[44:45]
	v_pk_mul_f32 v[42:43], v[42:43], v[46:47]
	v_pk_mul_f32 v[32:33], v[32:33], v[36:37]
	v_pk_mul_f32 v[34:35], v[34:35], v[38:39]
	v_cvt_pk_bf16_f32 v40, v40, v41
	v_cvt_pk_bf16_f32 v41, v42, v43
	v_cvt_pk_bf16_f32 v42, v32, v33
	v_cvt_pk_bf16_f32 v43, v34, v35
	global_store_dwordx4 v[146:147], v[40:43], off
	v_lshl_add_u64 v[146:147], v[146:147], 0, s[20:21]
	v_pk_mul_f32 v[150:151], v[28:29], s[46:47]
	v_pk_mul_f32 v[152:153], v[30:31], s[46:47]
	v_pk_mul_f32 v[154:155], v[20:21], s[46:47]
	v_pk_mul_f32 v[156:157], v[22:23], s[46:47]
	v_exp_f32_e32 v150, v150
	v_exp_f32_e32 v151, v151
	v_exp_f32_e32 v152, v152
	v_exp_f32_e32 v153, v153
	v_exp_f32_e32 v154, v154
	v_exp_f32_e32 v155, v155
	v_exp_f32_e32 v156, v156
	v_exp_f32_e32 v157, v157
	v_pk_add_f32 v[150:151], v[150:151], 1.0 op_sel_hi:[1,0]
	v_pk_add_f32 v[152:153], v[152:153], 1.0 op_sel_hi:[1,0]
	v_pk_add_f32 v[154:155], v[154:155], 1.0 op_sel_hi:[1,0]
	v_pk_add_f32 v[156:157], v[156:157], 1.0 op_sel_hi:[1,0]
	v_rcp_f32_e32 v150, v150
	v_rcp_f32_e32 v151, v151
	v_rcp_f32_e32 v152, v152
	v_rcp_f32_e32 v153, v153
	v_rcp_f32_e32 v154, v154
	v_rcp_f32_e32 v155, v155
	v_rcp_f32_e32 v156, v156
	v_rcp_f32_e32 v157, v157
	v_pk_mul_f32 v[28:29], v[28:29], v[150:151]
	v_pk_mul_f32 v[30:31], v[30:31], v[152:153]
	v_pk_mul_f32 v[20:21], v[20:21], v[154:155]
	v_pk_mul_f32 v[22:23], v[22:23], v[156:157]
	v_pk_mul_f32 v[24:25], v[24:25], v[28:29]
	v_pk_mul_f32 v[26:27], v[26:27], v[30:31]
	v_pk_mul_f32 v[16:17], v[16:17], v[20:21]
	v_pk_mul_f32 v[18:19], v[18:19], v[22:23]
	v_cvt_pk_bf16_f32 v24, v24, v25
	v_cvt_pk_bf16_f32 v25, v26, v27
	v_cvt_pk_bf16_f32 v26, v16, v17
	v_cvt_pk_bf16_f32 v27, v18, v19
	global_store_dwordx4 v[146:147], v[24:27], off
	v_lshl_add_u64 v[146:147], v[146:147], 0, s[20:21]
	v_pk_mul_f32 v[150:151], v[12:13], s[46:47]
	v_pk_mul_f32 v[152:153], v[14:15], s[46:47]
	v_pk_mul_f32 v[154:155], v[4:5], s[46:47]
	v_pk_mul_f32 v[156:157], v[6:7], s[46:47]
	v_exp_f32_e32 v150, v150
	v_exp_f32_e32 v151, v151
	v_exp_f32_e32 v152, v152
	v_exp_f32_e32 v153, v153
	v_exp_f32_e32 v154, v154
	v_exp_f32_e32 v155, v155
	v_exp_f32_e32 v156, v156
	v_exp_f32_e32 v157, v157
	v_pk_add_f32 v[150:151], v[150:151], 1.0 op_sel_hi:[1,0]
	v_pk_add_f32 v[152:153], v[152:153], 1.0 op_sel_hi:[1,0]
	v_pk_add_f32 v[154:155], v[154:155], 1.0 op_sel_hi:[1,0]
	v_pk_add_f32 v[156:157], v[156:157], 1.0 op_sel_hi:[1,0]
	v_rcp_f32_e32 v150, v150
	v_rcp_f32_e32 v151, v151
	v_rcp_f32_e32 v152, v152
	v_rcp_f32_e32 v153, v153
	v_rcp_f32_e32 v154, v154
	v_rcp_f32_e32 v155, v155
	v_rcp_f32_e32 v156, v156
	v_rcp_f32_e32 v157, v157
	v_pk_mul_f32 v[12:13], v[12:13], v[150:151]
	v_pk_mul_f32 v[14:15], v[14:15], v[152:153]
	v_pk_mul_f32 v[4:5], v[4:5], v[154:155]
	v_pk_mul_f32 v[6:7], v[6:7], v[156:157]
	v_pk_mul_f32 v[8:9], v[8:9], v[12:13]
	v_pk_mul_f32 v[10:11], v[10:11], v[14:15]
	v_pk_mul_f32 v[0:1], v[0:1], v[4:5]
	v_pk_mul_f32 v[2:3], v[2:3], v[6:7]
	v_cvt_pk_bf16_f32 v8, v8, v9
	v_cvt_pk_bf16_f32 v9, v10, v11
	v_cvt_pk_bf16_f32 v10, v0, v1
	v_cvt_pk_bf16_f32 v11, v2, v3
	global_store_dwordx4 v[146:147], v[8:11], off
	s_mov_b64 s[18:19], -1
	s_andn2_b64 vcc, exec, s[0:1]
	s_cbranch_vccnz .LBB0_1781
	s_andn2_b64 vcc, exec, s[4:5]
	s_cbranch_vccnz .LBB0_1780
	s_barrier
	s_branch .LBB0_1780
